# grid barrier poll loops: s_sleep 3 instead of s_sleep 1 between polls (less polling traffic on the shared counter)
# speedup vs baseline: 1.0088x; 1.0066x over previous
.LBB0_124:
	s_sleep 3
	global_load_dword v2, v0, s[4:5] offset:32 sc1
	s_waitcnt vmcnt(0)
	v_and_b32_e32 v2, 0xffff0000, v2
	v_cmp_ne_u32_e32 vcc, v2, v1
	s_or_b64 s[6:7], vcc, s[6:7]
	s_andn2_b64 exec, exec, s[6:7]
	s_cbranch_execnz .LBB0_124

.LBB0_196:
	v_readlane_b32 s6, v239, 9
	v_readlane_b32 s7, v239, 10
	s_mov_b64 s[8:9], -1
	s_mov_b64 s[10:11], -1
	s_waitcnt lgkmcnt(0)
	s_nop 1
	global_load_dword v0, v165, s[6:7] sc1
	v_readlane_b32 s6, v239, 11
	v_readlane_b32 s7, v239, 12
	s_nop 4
	global_load_dword v1, v165, s[6:7] sc1
	v_readlane_b32 s6, v239, 13
	v_readlane_b32 s7, v239, 14
	s_waitcnt vmcnt(0)
	v_add_u32_e32 v16, v1, v0
	s_nop 2
	global_load_dword v2, v165, s[6:7] sc1
	v_readlane_b32 s6, v239, 15
	v_readlane_b32 s7, v239, 16
	s_waitcnt vmcnt(0)
	v_add_u32_e32 v16, v16, v2
	s_nop 2
	global_load_dword v3, v165, s[6:7] sc1
	v_readlane_b32 s6, v239, 17
	v_readlane_b32 s7, v239, 18
	s_waitcnt vmcnt(0)
	v_add_u32_e32 v16, v16, v3
	s_nop 2
	global_load_dword v4, v165, s[6:7] sc1
	v_readlane_b32 s6, v239, 19
	v_readlane_b32 s7, v239, 20
	s_waitcnt vmcnt(0)
	v_add_u32_e32 v16, v16, v4
	s_nop 2
	global_load_dword v5, v165, s[6:7] sc1
	v_readlane_b32 s6, v239, 21
	v_readlane_b32 s7, v239, 22
	s_waitcnt vmcnt(0)
	v_add_u32_e32 v16, v16, v5
	s_nop 2
	global_load_dword v6, v165, s[6:7] sc1
	v_readlane_b32 s6, v239, 23
	v_readlane_b32 s7, v239, 24
	s_nop 4
	global_load_dword v7, v165, s[6:7] sc1
	global_load_dword v8, v165, s[70:71] sc1
	global_load_dword v9, v165, s[74:75] sc1
	global_load_dword v10, v165, s[90:91] sc1
	global_load_dword v11, v165, s[92:93] sc1
	global_load_dword v12, v165, s[94:95] sc1
	global_load_dword v13, v165, s[96:97] sc1
	global_load_dword v14, v165, s[54:55] sc1
	global_load_dword v15, v165, s[56:57] sc1
	s_waitcnt vmcnt(9)
	v_add_u32_e32 v16, v16, v6
	s_waitcnt vmcnt(8)
	v_add_u32_e32 v16, v16, v7
	s_waitcnt vmcnt(7)
	v_add_u32_e32 v16, v16, v8
	s_waitcnt vmcnt(6)
	v_add_u32_e32 v16, v16, v9
	s_waitcnt vmcnt(5)
	v_add_u32_e32 v16, v16, v10
	s_waitcnt vmcnt(4)
	v_add_u32_e32 v16, v16, v11
	s_waitcnt vmcnt(3)
	v_add_u32_e32 v16, v16, v12
	s_waitcnt vmcnt(2)
	v_add_u32_e32 v16, v16, v13
	s_waitcnt vmcnt(1)
	v_add_u32_e32 v16, v16, v14
	s_waitcnt vmcnt(0)
	v_add_u32_e32 v16, v16, v15
	v_cmp_eq_u32_e32 vcc, s3, v16
	s_cbranch_vccnz .LBB0_195
	s_and_b32 s1, s0, 0xff
	s_cmp_eq_u32 s1, 0
	s_mov_b64 s[6:7], -1
	s_sleep 3
	s_cbranch_scc0 .LBB0_200
	v_readlane_b32 s6, v239, 7
	v_readlane_b32 s7, v239, 8
	s_nop 4
	global_load_dword v16, v165, s[6:7] sc1
	s_waitcnt vmcnt(0)
	v_cmp_eq_u32_e32 vcc, 0, v16
	s_cbranch_vccnz .LBB0_202
	s_mov_b64 s[6:7], 0

.LBB0_214:
	s_and_b32 s1, s0, 0xff
	s_mov_b64 s[16:17], -1
	s_cmp_lg_u32 s1, 0
	s_mov_b64 s[6:7], -1
	s_sleep 3
	s_cbranch_scc1 .LBB0_217
	v_readlane_b32 s6, v239, 7
	v_readlane_b32 s7, v239, 8
	s_nop 4
	global_load_dword v0, v165, s[6:7] sc1
	s_waitcnt vmcnt(0)
	v_cmp_eq_u32_e32 vcc, 0, v0
	s_cbranch_vccnz .LBB0_219
	s_mov_b64 s[6:7], 0
	s_mov_b64 s[20:21], -1

.LBB0_1280:
	v_readlane_b32 s4, v239, 9
	v_readlane_b32 s5, v239, 10
	s_mov_b64 s[8:9], -1
	s_waitcnt lgkmcnt(0)
	s_nop 2
	global_load_dword v0, v165, s[4:5] sc1
	v_readlane_b32 s4, v239, 11
	v_readlane_b32 s5, v239, 12
	s_nop 4
	global_load_dword v1, v165, s[4:5] sc1
	v_readlane_b32 s4, v239, 13
	v_readlane_b32 s5, v239, 14
	s_waitcnt vmcnt(0)
	v_add_u32_e32 v16, v1, v0
	s_nop 2
	global_load_dword v2, v165, s[4:5] sc1
	v_readlane_b32 s4, v239, 15
	v_readlane_b32 s5, v239, 16
	s_waitcnt vmcnt(0)
	v_add_u32_e32 v16, v16, v2
	s_nop 2
	global_load_dword v3, v165, s[4:5] sc1
	v_readlane_b32 s4, v239, 17
	v_readlane_b32 s5, v239, 18
	s_waitcnt vmcnt(0)
	v_add_u32_e32 v16, v16, v3
	s_nop 2
	global_load_dword v4, v165, s[4:5] sc1
	v_readlane_b32 s4, v239, 19
	v_readlane_b32 s5, v239, 20
	s_waitcnt vmcnt(0)
	v_add_u32_e32 v16, v16, v4
	s_nop 2
	global_load_dword v5, v165, s[4:5] sc1
	v_readlane_b32 s4, v239, 21
	v_readlane_b32 s5, v239, 22
	s_waitcnt vmcnt(0)
	v_add_u32_e32 v16, v16, v5
	s_nop 2
	global_load_dword v6, v165, s[4:5] sc1
	v_readlane_b32 s4, v239, 23
	v_readlane_b32 s5, v239, 24
	s_nop 4
	global_load_dword v7, v165, s[4:5] sc1
	global_load_dword v8, v165, s[70:71] sc1
	global_load_dword v9, v165, s[74:75] sc1
	global_load_dword v10, v165, s[90:91] sc1
	global_load_dword v11, v165, s[92:93] sc1
	global_load_dword v12, v165, s[94:95] sc1
	global_load_dword v13, v165, s[96:97] sc1
	global_load_dword v14, v165, s[54:55] sc1
	global_load_dword v15, v165, s[56:57] sc1
	s_mov_b64 s[4:5], -1
	s_waitcnt vmcnt(9)
	v_add_u32_e32 v16, v16, v6
	s_waitcnt vmcnt(8)
	v_add_u32_e32 v16, v16, v7
	s_waitcnt vmcnt(7)
	v_add_u32_e32 v16, v16, v8
	s_waitcnt vmcnt(6)
	v_add_u32_e32 v16, v16, v9
	s_waitcnt vmcnt(5)
	v_add_u32_e32 v16, v16, v10
	s_waitcnt vmcnt(4)
	v_add_u32_e32 v16, v16, v11
	s_waitcnt vmcnt(3)
	v_add_u32_e32 v16, v16, v12
	s_waitcnt vmcnt(2)
	v_add_u32_e32 v16, v16, v13
	s_waitcnt vmcnt(1)
	v_add_u32_e32 v16, v16, v14
	s_waitcnt vmcnt(0)
	v_add_u32_e32 v16, v16, v15
	v_cmp_eq_u32_e32 vcc, s3, v16
	s_cbranch_vccnz .LBB0_1279
	s_and_b32 s4, s2, 0xff
	s_cmp_eq_u32 s4, 0
	s_mov_b64 s[4:5], -1
	s_mov_b64 s[6:7], -1
	s_sleep 3
	s_cbranch_scc0 .LBB0_1284
	v_readlane_b32 s4, v239, 7
	v_readlane_b32 s5, v239, 8
	s_nop 4
	global_load_dword v16, v165, s[4:5] sc1
	s_waitcnt vmcnt(0)
	v_cmp_eq_u32_e32 vcc, 0, v16
	s_cbranch_vccnz .LBB0_1286
	s_mov_b64 s[6:7], 0
	s_mov_b64 s[4:5], -1

.LBB0_1298:
	s_and_b32 s6, s2, 0xff
	s_mov_b64 s[14:15], -1
	s_cmp_lg_u32 s6, 0
	s_mov_b64 s[6:7], -1
	s_sleep 3
	s_cbranch_scc1 .LBB0_1301
	v_readlane_b32 s6, v239, 7
	v_readlane_b32 s7, v239, 8
	s_nop 4
	global_load_dword v0, v165, s[6:7] sc1
	s_waitcnt vmcnt(0)
	v_cmp_eq_u32_e32 vcc, 0, v0
	s_cbranch_vccnz .LBB0_1303
	s_mov_b64 s[6:7], 0
	s_mov_b64 s[16:17], -1
